# GEMM unit start: accumulator zeroing with 64 v_mov_b64 instead of 128 v_mov_b32
# speedup vs baseline: 1.0458x; 1.0037x over previous
.Lzskip_1:
	s_add_u32 s0, s6, 0x80
	s_addc_u32 s1, s7, 0
	s_add_u32 s6, s4, 0x100
	v_mov_b64_e32 v[0:1], 0
	s_addc_u32 s7, s5, 0
	s_mov_b32 s4, 0
	v_mov_b64_e32 v[2:3], 0
	v_mov_b64_e32 v[8:9], 0
	v_mov_b64_e32 v[10:11], 0
	v_mov_b64_e32 v[16:17], 0
	v_mov_b64_e32 v[18:19], 0
	v_mov_b64_e32 v[24:25], 0
	v_mov_b64_e32 v[26:27], 0
	v_mov_b64_e32 v[32:33], 0
	v_mov_b64_e32 v[34:35], 0
	v_mov_b64_e32 v[40:41], 0
	v_mov_b64_e32 v[42:43], 0
	v_mov_b64_e32 v[48:49], 0
	v_mov_b64_e32 v[50:51], 0
	v_mov_b64_e32 v[56:57], 0
	v_mov_b64_e32 v[58:59], 0
	v_mov_b64_e32 v[4:5], 0
	v_mov_b64_e32 v[6:7], 0
	v_mov_b64_e32 v[12:13], 0
	v_mov_b64_e32 v[14:15], 0
	v_mov_b64_e32 v[20:21], 0
	v_mov_b64_e32 v[22:23], 0
	v_mov_b64_e32 v[28:29], 0
	v_mov_b64_e32 v[30:31], 0
	v_mov_b64_e32 v[36:37], 0
	v_mov_b64_e32 v[38:39], 0
	v_mov_b64_e32 v[44:45], 0
	v_mov_b64_e32 v[46:47], 0
	v_mov_b64_e32 v[52:53], 0
	v_mov_b64_e32 v[54:55], 0
	v_mov_b64_e32 v[60:61], 0
	v_mov_b64_e32 v[62:63], 0
	v_mov_b64_e32 v[64:65], 0
	v_mov_b64_e32 v[66:67], 0
	v_mov_b64_e32 v[72:73], 0
	v_mov_b64_e32 v[74:75], 0
	v_mov_b64_e32 v[80:81], 0
	v_mov_b64_e32 v[82:83], 0
	v_mov_b64_e32 v[88:89], 0
	v_mov_b64_e32 v[90:91], 0
	v_mov_b64_e32 v[96:97], 0
	v_mov_b64_e32 v[98:99], 0
	v_mov_b64_e32 v[104:105], 0
	v_mov_b64_e32 v[106:107], 0
	v_mov_b64_e32 v[112:113], 0
	v_mov_b64_e32 v[114:115], 0
	v_mov_b64_e32 v[124:125], 0
	v_mov_b64_e32 v[126:127], 0
	v_mov_b64_e32 v[68:69], 0
	v_mov_b64_e32 v[70:71], 0
	v_mov_b64_e32 v[76:77], 0
	v_mov_b64_e32 v[78:79], 0
	v_mov_b64_e32 v[84:85], 0
	v_mov_b64_e32 v[86:87], 0
	v_mov_b64_e32 v[92:93], 0
	v_mov_b64_e32 v[94:95], 0
	v_mov_b64_e32 v[100:101], 0
	v_mov_b64_e32 v[102:103], 0
	v_mov_b64_e32 v[108:109], 0
	v_mov_b64_e32 v[110:111], 0
	v_mov_b64_e32 v[116:117], 0
	v_mov_b64_e32 v[118:119], 0
	v_mov_b64_e32 v[120:121], 0
	v_mov_b64_e32 v[122:123], 0

.Lzskip_2:
	s_add_u32 s24, s24, 0x80
	s_addc_u32 s25, s25, 0
	s_add_u32 s86, s28, 0x100
	v_mov_b64_e32 v[0:1], 0
	s_addc_u32 s87, s29, 0
	s_mov_b32 s28, 0
	v_mov_b64_e32 v[2:3], 0
	v_mov_b64_e32 v[4:5], 0
	v_mov_b64_e32 v[6:7], 0
	v_mov_b64_e32 v[16:17], 0
	v_mov_b64_e32 v[18:19], 0
	v_mov_b64_e32 v[20:21], 0
	v_mov_b64_e32 v[22:23], 0
	v_mov_b64_e32 v[32:33], 0
	v_mov_b64_e32 v[34:35], 0
	v_mov_b64_e32 v[36:37], 0
	v_mov_b64_e32 v[38:39], 0
	v_mov_b64_e32 v[48:49], 0
	v_mov_b64_e32 v[50:51], 0
	v_mov_b64_e32 v[52:53], 0
	v_mov_b64_e32 v[54:55], 0
	v_mov_b64_e32 v[8:9], 0
	v_mov_b64_e32 v[10:11], 0
	v_mov_b64_e32 v[12:13], 0
	v_mov_b64_e32 v[14:15], 0
	v_mov_b64_e32 v[24:25], 0
	v_mov_b64_e32 v[26:27], 0
	v_mov_b64_e32 v[28:29], 0
	v_mov_b64_e32 v[30:31], 0
	v_mov_b64_e32 v[40:41], 0
	v_mov_b64_e32 v[42:43], 0
	v_mov_b64_e32 v[44:45], 0
	v_mov_b64_e32 v[46:47], 0
	v_mov_b64_e32 v[56:57], 0
	v_mov_b64_e32 v[58:59], 0
	v_mov_b64_e32 v[60:61], 0
	v_mov_b64_e32 v[62:63], 0
	v_mov_b64_e32 v[64:65], 0
	v_mov_b64_e32 v[66:67], 0
	v_mov_b64_e32 v[68:69], 0
	v_mov_b64_e32 v[70:71], 0
	v_mov_b64_e32 v[80:81], 0
	v_mov_b64_e32 v[82:83], 0
	v_mov_b64_e32 v[84:85], 0
	v_mov_b64_e32 v[86:87], 0
	v_mov_b64_e32 v[96:97], 0
	v_mov_b64_e32 v[98:99], 0
	v_mov_b64_e32 v[100:101], 0
	v_mov_b64_e32 v[102:103], 0
	v_mov_b64_e32 v[112:113], 0
	v_mov_b64_e32 v[114:115], 0
	v_mov_b64_e32 v[116:117], 0
	v_mov_b64_e32 v[118:119], 0
	v_mov_b64_e32 v[72:73], 0
	v_mov_b64_e32 v[74:75], 0
	v_mov_b64_e32 v[76:77], 0
	v_mov_b64_e32 v[78:79], 0
	v_mov_b64_e32 v[88:89], 0
	v_mov_b64_e32 v[90:91], 0
	v_mov_b64_e32 v[92:93], 0
	v_mov_b64_e32 v[94:95], 0
	v_mov_b64_e32 v[104:105], 0
	v_mov_b64_e32 v[106:107], 0
	v_mov_b64_e32 v[108:109], 0
	v_mov_b64_e32 v[110:111], 0
	v_mov_b64_e32 v[120:121], 0
	v_mov_b64_e32 v[122:123], 0
	v_mov_b64_e32 v[124:125], 0
	v_mov_b64_e32 v[126:127], 0

.Lzskip_3:
	s_add_u32 s24, s24, 0x80
	s_addc_u32 s25, s25, 0
	s_add_u32 s68, s28, 0x100
	v_mov_b64_e32 v[0:1], 0
	s_addc_u32 s69, s29, 0
	s_mov_b32 s28, 0
	v_mov_b64_e32 v[2:3], 0
	v_mov_b64_e32 v[4:5], 0
	v_mov_b64_e32 v[6:7], 0
	v_mov_b64_e32 v[16:17], 0
	v_mov_b64_e32 v[18:19], 0
	v_mov_b64_e32 v[20:21], 0
	v_mov_b64_e32 v[22:23], 0
	v_mov_b64_e32 v[32:33], 0
	v_mov_b64_e32 v[34:35], 0
	v_mov_b64_e32 v[36:37], 0
	v_mov_b64_e32 v[38:39], 0
	v_mov_b64_e32 v[48:49], 0
	v_mov_b64_e32 v[50:51], 0
	v_mov_b64_e32 v[52:53], 0
	v_mov_b64_e32 v[54:55], 0
	v_mov_b64_e32 v[8:9], 0
	v_mov_b64_e32 v[10:11], 0
	v_mov_b64_e32 v[12:13], 0
	v_mov_b64_e32 v[14:15], 0
	v_mov_b64_e32 v[24:25], 0
	v_mov_b64_e32 v[26:27], 0
	v_mov_b64_e32 v[28:29], 0
	v_mov_b64_e32 v[30:31], 0
	v_mov_b64_e32 v[40:41], 0
	v_mov_b64_e32 v[42:43], 0
	v_mov_b64_e32 v[44:45], 0
	v_mov_b64_e32 v[46:47], 0
	v_mov_b64_e32 v[56:57], 0
	v_mov_b64_e32 v[58:59], 0
	v_mov_b64_e32 v[60:61], 0
	v_mov_b64_e32 v[62:63], 0
	v_mov_b64_e32 v[64:65], 0
	v_mov_b64_e32 v[66:67], 0
	v_mov_b64_e32 v[68:69], 0
	v_mov_b64_e32 v[70:71], 0
	v_mov_b64_e32 v[80:81], 0
	v_mov_b64_e32 v[82:83], 0
	v_mov_b64_e32 v[84:85], 0
	v_mov_b64_e32 v[86:87], 0
	v_mov_b64_e32 v[96:97], 0
	v_mov_b64_e32 v[98:99], 0
	v_mov_b64_e32 v[100:101], 0
	v_mov_b64_e32 v[102:103], 0
	v_mov_b64_e32 v[112:113], 0
	v_mov_b64_e32 v[114:115], 0
	v_mov_b64_e32 v[116:117], 0
	v_mov_b64_e32 v[118:119], 0
	v_mov_b64_e32 v[72:73], 0
	v_mov_b64_e32 v[74:75], 0
	v_mov_b64_e32 v[76:77], 0
	v_mov_b64_e32 v[78:79], 0
	v_mov_b64_e32 v[88:89], 0
	v_mov_b64_e32 v[90:91], 0
	v_mov_b64_e32 v[92:93], 0
	v_mov_b64_e32 v[94:95], 0
	v_mov_b64_e32 v[104:105], 0
	v_mov_b64_e32 v[106:107], 0
	v_mov_b64_e32 v[108:109], 0
	v_mov_b64_e32 v[110:111], 0
	v_mov_b64_e32 v[124:125], 0
	v_mov_b64_e32 v[126:127], 0
	v_mov_b64_e32 v[120:121], 0
	v_mov_b64_e32 v[122:123], 0

.Lzskip_4:
	s_add_u32 s24, s24, 0x80
	s_addc_u32 s25, s25, 0
	s_add_u32 s16, s28, 0x100
	v_mov_b64_e32 v[0:1], 0
	s_addc_u32 s20, s29, 0
	s_mov_b32 s26, 0
	v_mov_b64_e32 v[2:3], 0
	v_mov_b64_e32 v[4:5], 0
	v_mov_b64_e32 v[6:7], 0
	v_mov_b64_e32 v[16:17], 0
	v_mov_b64_e32 v[18:19], 0
	v_mov_b64_e32 v[20:21], 0
	v_mov_b64_e32 v[22:23], 0
	v_mov_b64_e32 v[32:33], 0
	v_mov_b64_e32 v[34:35], 0
	v_mov_b64_e32 v[36:37], 0
	v_mov_b64_e32 v[38:39], 0
	v_mov_b64_e32 v[48:49], 0
	v_mov_b64_e32 v[50:51], 0
	v_mov_b64_e32 v[52:53], 0
	v_mov_b64_e32 v[54:55], 0
	v_mov_b64_e32 v[8:9], 0
	v_mov_b64_e32 v[10:11], 0
	v_mov_b64_e32 v[12:13], 0
	v_mov_b64_e32 v[14:15], 0
	v_mov_b64_e32 v[24:25], 0
	v_mov_b64_e32 v[26:27], 0
	v_mov_b64_e32 v[28:29], 0
	v_mov_b64_e32 v[30:31], 0
	v_mov_b64_e32 v[40:41], 0
	v_mov_b64_e32 v[42:43], 0
	v_mov_b64_e32 v[44:45], 0
	v_mov_b64_e32 v[46:47], 0
	v_mov_b64_e32 v[56:57], 0
	v_mov_b64_e32 v[58:59], 0
	v_mov_b64_e32 v[60:61], 0
	v_mov_b64_e32 v[62:63], 0
	v_mov_b64_e32 v[64:65], 0
	v_mov_b64_e32 v[66:67], 0
	v_mov_b64_e32 v[68:69], 0
	v_mov_b64_e32 v[70:71], 0
	v_mov_b64_e32 v[80:81], 0
	v_mov_b64_e32 v[82:83], 0
	v_mov_b64_e32 v[84:85], 0
	v_mov_b64_e32 v[86:87], 0
	v_mov_b64_e32 v[96:97], 0
	v_mov_b64_e32 v[98:99], 0
	v_mov_b64_e32 v[100:101], 0
	v_mov_b64_e32 v[102:103], 0
	v_mov_b64_e32 v[116:117], 0
	v_mov_b64_e32 v[118:119], 0
	v_mov_b64_e32 v[124:125], 0
	v_mov_b64_e32 v[126:127], 0
	v_mov_b64_e32 v[72:73], 0
	v_mov_b64_e32 v[74:75], 0
	v_mov_b64_e32 v[76:77], 0
	v_mov_b64_e32 v[78:79], 0
	v_mov_b64_e32 v[88:89], 0
	v_mov_b64_e32 v[90:91], 0
	v_mov_b64_e32 v[92:93], 0
	v_mov_b64_e32 v[94:95], 0
	v_mov_b64_e32 v[104:105], 0
	v_mov_b64_e32 v[106:107], 0
	v_mov_b64_e32 v[108:109], 0
	v_mov_b64_e32 v[110:111], 0
	v_mov_b64_e32 v[132:133], 0
	v_mov_b64_e32 v[134:135], 0
	v_mov_b64_e32 v[144:145], 0
	v_mov_b64_e32 v[146:147], 0

.Lzskip_5:
	s_add_u32 s24, s24, 0x80
	s_addc_u32 s25, s25, 0
	s_add_u32 s73, s28, 0x100
	v_mov_b64_e32 v[0:1], 0
	s_addc_u32 s82, s29, 0
	s_mov_b32 s28, 0
	v_mov_b64_e32 v[2:3], 0
	v_mov_b64_e32 v[4:5], 0
	v_mov_b64_e32 v[6:7], 0
	v_mov_b64_e32 v[16:17], 0
	v_mov_b64_e32 v[18:19], 0
	v_mov_b64_e32 v[20:21], 0
	v_mov_b64_e32 v[22:23], 0
	v_mov_b64_e32 v[32:33], 0
	v_mov_b64_e32 v[34:35], 0
	v_mov_b64_e32 v[36:37], 0
	v_mov_b64_e32 v[38:39], 0
	v_mov_b64_e32 v[48:49], 0
	v_mov_b64_e32 v[50:51], 0
	v_mov_b64_e32 v[52:53], 0
	v_mov_b64_e32 v[54:55], 0
	v_mov_b64_e32 v[8:9], 0
	v_mov_b64_e32 v[10:11], 0
	v_mov_b64_e32 v[12:13], 0
	v_mov_b64_e32 v[14:15], 0
	v_mov_b64_e32 v[24:25], 0
	v_mov_b64_e32 v[26:27], 0
	v_mov_b64_e32 v[28:29], 0
	v_mov_b64_e32 v[30:31], 0
	v_mov_b64_e32 v[40:41], 0
	v_mov_b64_e32 v[42:43], 0
	v_mov_b64_e32 v[44:45], 0
	v_mov_b64_e32 v[46:47], 0
	v_mov_b64_e32 v[56:57], 0
	v_mov_b64_e32 v[58:59], 0
	v_mov_b64_e32 v[60:61], 0
	v_mov_b64_e32 v[62:63], 0
	v_mov_b64_e32 v[64:65], 0
	v_mov_b64_e32 v[66:67], 0
	v_mov_b64_e32 v[68:69], 0
	v_mov_b64_e32 v[70:71], 0
	v_mov_b64_e32 v[80:81], 0
	v_mov_b64_e32 v[82:83], 0
	v_mov_b64_e32 v[84:85], 0
	v_mov_b64_e32 v[86:87], 0
	v_mov_b64_e32 v[96:97], 0
	v_mov_b64_e32 v[98:99], 0
	v_mov_b64_e32 v[100:101], 0
	v_mov_b64_e32 v[102:103], 0
	v_mov_b64_e32 v[112:113], 0
	v_mov_b64_e32 v[114:115], 0
	v_mov_b64_e32 v[116:117], 0
	v_mov_b64_e32 v[118:119], 0
	v_mov_b64_e32 v[72:73], 0
	v_mov_b64_e32 v[74:75], 0
	v_mov_b64_e32 v[76:77], 0
	v_mov_b64_e32 v[78:79], 0
	v_mov_b64_e32 v[88:89], 0
	v_mov_b64_e32 v[90:91], 0
	v_mov_b64_e32 v[92:93], 0
	v_mov_b64_e32 v[94:95], 0
	v_mov_b64_e32 v[104:105], 0
	v_mov_b64_e32 v[106:107], 0
	v_mov_b64_e32 v[108:109], 0
	v_mov_b64_e32 v[110:111], 0
	v_mov_b64_e32 v[124:125], 0
	v_mov_b64_e32 v[126:127], 0
	v_mov_b64_e32 v[120:121], 0
	v_mov_b64_e32 v[122:123], 0

.Lzskip_6:
	s_add_u32 s4, s28, 0x80
	s_addc_u32 s5, s29, 0
	s_add_u32 s28, s24, 0x100
	v_mov_b64_e32 v[0:1], 0
	s_addc_u32 s29, s25, 0
	s_mov_b32 s24, 0
	v_mov_b64_e32 v[2:3], 0
	v_mov_b64_e32 v[4:5], 0
	v_mov_b64_e32 v[6:7], 0
	v_mov_b64_e32 v[16:17], 0
	v_mov_b64_e32 v[18:19], 0
	v_mov_b64_e32 v[20:21], 0
	v_mov_b64_e32 v[22:23], 0
	v_mov_b64_e32 v[32:33], 0
	v_mov_b64_e32 v[34:35], 0
	v_mov_b64_e32 v[36:37], 0
	v_mov_b64_e32 v[38:39], 0
	v_mov_b64_e32 v[48:49], 0
	v_mov_b64_e32 v[50:51], 0
	v_mov_b64_e32 v[52:53], 0
	v_mov_b64_e32 v[54:55], 0
	v_mov_b64_e32 v[8:9], 0
	v_mov_b64_e32 v[10:11], 0
	v_mov_b64_e32 v[12:13], 0
	v_mov_b64_e32 v[14:15], 0
	v_mov_b64_e32 v[24:25], 0
	v_mov_b64_e32 v[26:27], 0
	v_mov_b64_e32 v[28:29], 0
	v_mov_b64_e32 v[30:31], 0
	v_mov_b64_e32 v[40:41], 0
	v_mov_b64_e32 v[42:43], 0
	v_mov_b64_e32 v[44:45], 0
	v_mov_b64_e32 v[46:47], 0
	v_mov_b64_e32 v[56:57], 0
	v_mov_b64_e32 v[58:59], 0
	v_mov_b64_e32 v[60:61], 0
	v_mov_b64_e32 v[62:63], 0
	v_mov_b64_e32 v[64:65], 0
	v_mov_b64_e32 v[66:67], 0
	v_mov_b64_e32 v[68:69], 0
	v_mov_b64_e32 v[70:71], 0
	v_mov_b64_e32 v[80:81], 0
	v_mov_b64_e32 v[82:83], 0
	v_mov_b64_e32 v[84:85], 0
	v_mov_b64_e32 v[86:87], 0
	v_mov_b64_e32 v[96:97], 0
	v_mov_b64_e32 v[98:99], 0
	v_mov_b64_e32 v[100:101], 0
	v_mov_b64_e32 v[102:103], 0
	v_mov_b64_e32 v[112:113], 0
	v_mov_b64_e32 v[114:115], 0
	v_mov_b64_e32 v[116:117], 0
	v_mov_b64_e32 v[118:119], 0
	v_mov_b64_e32 v[72:73], 0
	v_mov_b64_e32 v[74:75], 0
	v_mov_b64_e32 v[76:77], 0
	v_mov_b64_e32 v[78:79], 0
	v_mov_b64_e32 v[88:89], 0
	v_mov_b64_e32 v[90:91], 0
	v_mov_b64_e32 v[92:93], 0
	v_mov_b64_e32 v[94:95], 0
	v_mov_b64_e32 v[104:105], 0
	v_mov_b64_e32 v[106:107], 0
	v_mov_b64_e32 v[108:109], 0
	v_mov_b64_e32 v[110:111], 0
	v_mov_b64_e32 v[120:121], 0
	v_mov_b64_e32 v[122:123], 0
	v_mov_b64_e32 v[124:125], 0
	v_mov_b64_e32 v[126:127], 0

.Lzskip_7:
	s_add_u32 s24, s24, 0x80
	s_addc_u32 s25, s25, 0
	s_add_u32 s55, s28, 0x100
	v_mov_b64_e32 v[0:1], 0
	s_addc_u32 s72, s29, 0
	s_mov_b32 s28, 0
	v_mov_b64_e32 v[2:3], 0
	v_mov_b64_e32 v[4:5], 0
	v_mov_b64_e32 v[6:7], 0
	v_mov_b64_e32 v[16:17], 0
	v_mov_b64_e32 v[18:19], 0
	v_mov_b64_e32 v[20:21], 0
	v_mov_b64_e32 v[22:23], 0
	v_mov_b64_e32 v[32:33], 0
	v_mov_b64_e32 v[34:35], 0
	v_mov_b64_e32 v[36:37], 0
	v_mov_b64_e32 v[38:39], 0
	v_mov_b64_e32 v[48:49], 0
	v_mov_b64_e32 v[50:51], 0
	v_mov_b64_e32 v[52:53], 0
	v_mov_b64_e32 v[54:55], 0
	v_mov_b64_e32 v[8:9], 0
	v_mov_b64_e32 v[10:11], 0
	v_mov_b64_e32 v[12:13], 0
	v_mov_b64_e32 v[14:15], 0
	v_mov_b64_e32 v[24:25], 0
	v_mov_b64_e32 v[26:27], 0
	v_mov_b64_e32 v[28:29], 0
	v_mov_b64_e32 v[30:31], 0
	v_mov_b64_e32 v[40:41], 0
	v_mov_b64_e32 v[42:43], 0
	v_mov_b64_e32 v[44:45], 0
	v_mov_b64_e32 v[46:47], 0
	v_mov_b64_e32 v[56:57], 0
	v_mov_b64_e32 v[58:59], 0
	v_mov_b64_e32 v[60:61], 0
	v_mov_b64_e32 v[62:63], 0
	v_mov_b64_e32 v[64:65], 0
	v_mov_b64_e32 v[66:67], 0
	v_mov_b64_e32 v[68:69], 0
	v_mov_b64_e32 v[70:71], 0
	v_mov_b64_e32 v[80:81], 0
	v_mov_b64_e32 v[82:83], 0
	v_mov_b64_e32 v[84:85], 0
	v_mov_b64_e32 v[86:87], 0
	v_mov_b64_e32 v[96:97], 0
	v_mov_b64_e32 v[98:99], 0
	v_mov_b64_e32 v[100:101], 0
	v_mov_b64_e32 v[102:103], 0
	v_mov_b64_e32 v[112:113], 0
	v_mov_b64_e32 v[114:115], 0
	v_mov_b64_e32 v[116:117], 0
	v_mov_b64_e32 v[118:119], 0
	v_mov_b64_e32 v[72:73], 0
	v_mov_b64_e32 v[74:75], 0
	v_mov_b64_e32 v[76:77], 0
	v_mov_b64_e32 v[78:79], 0
	v_mov_b64_e32 v[88:89], 0
	v_mov_b64_e32 v[90:91], 0
	v_mov_b64_e32 v[92:93], 0
	v_mov_b64_e32 v[94:95], 0
	v_mov_b64_e32 v[104:105], 0
	v_mov_b64_e32 v[106:107], 0
	v_mov_b64_e32 v[108:109], 0
	v_mov_b64_e32 v[110:111], 0
	v_mov_b64_e32 v[124:125], 0
	v_mov_b64_e32 v[126:127], 0
	v_mov_b64_e32 v[120:121], 0
	v_mov_b64_e32 v[122:123], 0

.Lzskip_8:
	s_add_u32 s28, s28, 0x80
	s_addc_u32 s29, s29, 0
	s_add_u32 s48, s48, 0x100
	v_mov_b64_e32 v[0:1], 0
	s_addc_u32 s49, s49, 0
	s_mov_b32 s30, 0
	v_mov_b64_e32 v[2:3], 0
	v_mov_b64_e32 v[4:5], 0
	v_mov_b64_e32 v[6:7], 0
	v_mov_b64_e32 v[16:17], 0
	v_mov_b64_e32 v[18:19], 0
	v_mov_b64_e32 v[20:21], 0
	v_mov_b64_e32 v[22:23], 0
	v_mov_b64_e32 v[32:33], 0
	v_mov_b64_e32 v[34:35], 0
	v_mov_b64_e32 v[36:37], 0
	v_mov_b64_e32 v[38:39], 0
	v_mov_b64_e32 v[48:49], 0
	v_mov_b64_e32 v[50:51], 0
	v_mov_b64_e32 v[52:53], 0
	v_mov_b64_e32 v[54:55], 0
	v_mov_b64_e32 v[8:9], 0
	v_mov_b64_e32 v[10:11], 0
	v_mov_b64_e32 v[12:13], 0
	v_mov_b64_e32 v[14:15], 0
	v_mov_b64_e32 v[24:25], 0
	v_mov_b64_e32 v[26:27], 0
	v_mov_b64_e32 v[28:29], 0
	v_mov_b64_e32 v[30:31], 0
	v_mov_b64_e32 v[40:41], 0
	v_mov_b64_e32 v[42:43], 0
	v_mov_b64_e32 v[44:45], 0
	v_mov_b64_e32 v[46:47], 0
	v_mov_b64_e32 v[56:57], 0
	v_mov_b64_e32 v[58:59], 0
	v_mov_b64_e32 v[60:61], 0
	v_mov_b64_e32 v[62:63], 0
	v_mov_b64_e32 v[64:65], 0
	v_mov_b64_e32 v[66:67], 0
	v_mov_b64_e32 v[68:69], 0
	v_mov_b64_e32 v[70:71], 0
	v_mov_b64_e32 v[80:81], 0
	v_mov_b64_e32 v[82:83], 0
	v_mov_b64_e32 v[84:85], 0
	v_mov_b64_e32 v[86:87], 0
	v_mov_b64_e32 v[96:97], 0
	v_mov_b64_e32 v[98:99], 0
	v_mov_b64_e32 v[100:101], 0
	v_mov_b64_e32 v[102:103], 0
	v_mov_b64_e32 v[112:113], 0
	v_mov_b64_e32 v[114:115], 0
	v_mov_b64_e32 v[116:117], 0
	v_mov_b64_e32 v[118:119], 0
	v_mov_b64_e32 v[72:73], 0
	v_mov_b64_e32 v[74:75], 0
	v_mov_b64_e32 v[76:77], 0
	v_mov_b64_e32 v[78:79], 0
	v_mov_b64_e32 v[88:89], 0
	v_mov_b64_e32 v[90:91], 0
	v_mov_b64_e32 v[92:93], 0
	v_mov_b64_e32 v[94:95], 0
	v_mov_b64_e32 v[104:105], 0
	v_mov_b64_e32 v[106:107], 0
	v_mov_b64_e32 v[108:109], 0
	v_mov_b64_e32 v[110:111], 0
	v_mov_b64_e32 v[124:125], 0
	v_mov_b64_e32 v[126:127], 0
	v_mov_b64_e32 v[120:121], 0
	v_mov_b64_e32 v[122:123], 0

.Lzskip_9:
	s_add_u32 s0, s24, 0x80
	s_addc_u32 s1, s25, 0
	s_add_u32 s24, s10, 0x100
	v_mov_b64_e32 v[0:1], 0
	s_addc_u32 s25, s11, 0
	s_mov_b32 s10, 0
	v_mov_b64_e32 v[2:3], 0
	v_mov_b64_e32 v[4:5], 0
	v_mov_b64_e32 v[6:7], 0
	v_mov_b64_e32 v[16:17], 0
	v_mov_b64_e32 v[18:19], 0
	v_mov_b64_e32 v[20:21], 0
	v_mov_b64_e32 v[22:23], 0
	v_mov_b64_e32 v[32:33], 0
	v_mov_b64_e32 v[34:35], 0
	v_mov_b64_e32 v[36:37], 0
	v_mov_b64_e32 v[38:39], 0
	v_mov_b64_e32 v[48:49], 0
	v_mov_b64_e32 v[50:51], 0
	v_mov_b64_e32 v[52:53], 0
	v_mov_b64_e32 v[54:55], 0
	v_mov_b64_e32 v[8:9], 0
	v_mov_b64_e32 v[10:11], 0
	v_mov_b64_e32 v[12:13], 0
	v_mov_b64_e32 v[14:15], 0
	v_mov_b64_e32 v[24:25], 0
	v_mov_b64_e32 v[26:27], 0
	v_mov_b64_e32 v[28:29], 0
	v_mov_b64_e32 v[30:31], 0
	v_mov_b64_e32 v[40:41], 0
	v_mov_b64_e32 v[42:43], 0
	v_mov_b64_e32 v[44:45], 0
	v_mov_b64_e32 v[46:47], 0
	v_mov_b64_e32 v[56:57], 0
	v_mov_b64_e32 v[58:59], 0
	v_mov_b64_e32 v[60:61], 0
	v_mov_b64_e32 v[62:63], 0
	v_mov_b64_e32 v[64:65], 0
	v_mov_b64_e32 v[66:67], 0
	v_mov_b64_e32 v[68:69], 0
	v_mov_b64_e32 v[70:71], 0
	v_mov_b64_e32 v[80:81], 0
	v_mov_b64_e32 v[82:83], 0
	v_mov_b64_e32 v[84:85], 0
	v_mov_b64_e32 v[86:87], 0
	v_mov_b64_e32 v[96:97], 0
	v_mov_b64_e32 v[98:99], 0
	v_mov_b64_e32 v[100:101], 0
	v_mov_b64_e32 v[102:103], 0
	v_mov_b64_e32 v[112:113], 0
	v_mov_b64_e32 v[114:115], 0
	v_mov_b64_e32 v[116:117], 0
	v_mov_b64_e32 v[118:119], 0
	v_mov_b64_e32 v[72:73], 0
	v_mov_b64_e32 v[74:75], 0
	v_mov_b64_e32 v[76:77], 0
	v_mov_b64_e32 v[78:79], 0
	v_mov_b64_e32 v[88:89], 0
	v_mov_b64_e32 v[90:91], 0
	v_mov_b64_e32 v[92:93], 0
	v_mov_b64_e32 v[94:95], 0
	v_mov_b64_e32 v[104:105], 0
	v_mov_b64_e32 v[106:107], 0
	v_mov_b64_e32 v[108:109], 0
	v_mov_b64_e32 v[110:111], 0
	v_mov_b64_e32 v[120:121], 0
	v_mov_b64_e32 v[122:123], 0
	v_mov_b64_e32 v[124:125], 0
	v_mov_b64_e32 v[126:127], 0
